# plus GEMM2 epilogue store tails: eight staged rows read from LDS together before the row stores
# baseline (speedup 1.0000x reference)
;     __device__ __forceinline__ bf16_t* G() const { return (bf16_t*)(ws + OFF_G); }
;     __device__ __forceinline__ bf16_t* Mb() const { return (bf16_t*)(ws + OFF_MB); }
; __device__ __forceinline__ int opaque_tid() { int t = threadIdx.x; asm volatile("" : "+v"(t)); return t; }
; __device__ __forceinline__ void phase_gemm2(const Params& p, int layer, LAS unsigned char* lds) {
;     ...
;         const int tid2 = opaque_tid(), lane2 = tid2 & 63, fr = lane2 & 15, fq = lane2 >> 4;
; #pragma unroll
;         for (int ai = 0; ai < 2; ai++) {
;             const int f0 = nt * 256 + ai * 128 + wr * 64;
;             epi_store_rows<true>(lds, wid, lane2, fr, fq, wc, mt, p.Mb() + f0, DM, [&](int bj, int n, int m) -> u32x2 {
;                 const int tk = mt * 256 + bj * 128 + wc * 32 + n * 16 + fr;
;                 const unsigned gw = *(const unsigned*)((const unsigned char*)p.G() + (size_t)tk * 3072 + 2048 + f0 + fq * 16 + m * 4);
;                 const f32x4 v = acc[ai][bj][m][n] * (1.f / 255.f);
.LBB0_578:
	v_mov_b32_e32 v130, v168
	s_or_b32 s0, s0, s40
	v_and_b32_e32 v0, 15, v130
	v_lshlrev_b32_e32 v131, 1, v130
	v_and_b32_e32 v131, 0x60, v131
	v_mul_u32_u24_e32 v132, 0x90, v0
	v_add3_u32 v155, s42, v131, v132
	v_lshlrev_b32_e32 v131, 4, v130
	v_bfe_u32 v132, v130, 3, 3
	v_or_b32_e32 v138, s0, v0
	v_and_b32_e32 v0, 48, v130
	v_and_b32_e32 v148, 0x70, v131
	v_mul_u32_u24_e32 v130, 0x90, v132
	v_add3_u32 v154, s42, v148, v130
	v_or_b32_e32 v130, s0, v132
	v_ashrrev_i32_e32 v131, 31, v130
	v_or_b32_e32 v133, 8, v132
	v_lshlrev_b64 v[146:147], 11, v[130:131]
	v_or_b32_e32 v130, s0, v133
	v_ashrrev_i32_e32 v131, 31, v130
	v_or_b32_e32 v139, 16, v132
	v_lshlrev_b64 v[144:145], 11, v[130:131]
	v_or_b32_e32 v130, s0, v139
	v_ashrrev_i32_e32 v131, 31, v130
	v_or_b32_e32 v150, 24, v132
	v_lshlrev_b64 v[142:143], 11, v[130:131]
	v_or_b32_e32 v130, s0, v150
	v_ashrrev_i32_e32 v131, 31, v130
	s_bitset1_b32 s0, 7
	v_lshlrev_b64 v[140:141], 11, v[130:131]
	v_or_b32_e32 v130, s0, v132
	v_ashrrev_i32_e32 v131, 31, v130
	v_lshlrev_b64 v[136:137], 11, v[130:131]
	v_or_b32_e32 v130, s0, v133
	s_add_i32 s4, s67, s3
	v_ashrrev_i32_e32 v131, 31, v130
	v_mov_b64_e32 v[152:153], s[20:21]
	v_or_b32_e32 v157, 16, v138
	v_or_b32_e32 v156, 0x80, v138
	v_or_b32_e32 v149, 0x90, v138
	v_lshlrev_b64 v[134:135], 11, v[130:131]
	v_or_b32_e32 v130, s0, v139
	s_ashr_i32 s5, s4, 31
	v_mad_i64_i32 v[138:139], s[6:7], v138, s90, v[152:153]
	v_lshl_add_u64 v[138:139], v[138:139], 0, s[4:5]
	v_ashrrev_i32_e32 v131, 31, v130
	v_lshl_add_u64 v[138:139], v[138:139], 0, v[0:1]
	s_mov_b64 s[8:9], 0x17e3e900
	v_lshlrev_b64 v[132:133], 11, v[130:131]
	v_or_b32_e32 v130, s0, v150
	v_lshl_add_u64 v[150:151], v[138:139], 0, s[8:9]
	v_add_co_u32_e32 v138, vcc, s81, v138
	v_pk_mul_f32 v[126:127], v[126:127], s[2:3] op_sel_hi:[1,0]
	s_nop 0
	v_addc_co_u32_e32 v139, vcc, 0, v139, vcc
	global_load_dwordx4 v[192:195], v[150:151], off
	global_load_dwordx4 v[196:199], v[150:151], off offset:128
	v_mad_i64_i32 v[162:163], s[6:7], v157, s90, v[152:153]
	v_lshl_add_u64 v[162:163], v[162:163], 0, s[4:5]
	v_lshl_add_u64 v[162:163], v[162:163], 0, v[0:1]
	v_lshl_add_u64 v[162:163], v[162:163], 0, s[8:9]
	global_load_dwordx4 v[200:203], v[162:163], off
	global_load_dwordx4 v[204:207], v[162:163], off offset:128
	v_mad_i64_i32 v[162:163], s[6:7], v156, s90, v[152:153]
	v_lshl_add_u64 v[162:163], v[162:163], 0, s[4:5]
	v_lshl_add_u64 v[162:163], v[162:163], 0, v[0:1]
	v_lshl_add_u64 v[162:163], v[162:163], 0, s[8:9]
	global_load_dwordx4 v[208:211], v[162:163], off
	global_load_dwordx4 v[212:215], v[162:163], off offset:128
	v_mad_i64_i32 v[162:163], s[6:7], v149, s90, v[152:153]
	v_lshl_add_u64 v[162:163], v[162:163], 0, s[4:5]
	v_lshl_add_u64 v[162:163], v[162:163], 0, v[0:1]
	v_lshl_add_u64 v[162:163], v[162:163], 0, s[8:9]
	global_load_dwordx4 v[216:219], v[162:163], off
	global_load_dwordx4 v[220:223], v[162:163], off offset:128
	v_pk_mul_f32 v[128:129], v[128:129], s[2:3] op_sel_hi:[1,0]
	v_pk_mul_f32 v[122:123], v[122:123], s[2:3] op_sel_hi:[1,0]
	v_pk_mul_f32 v[124:125], v[124:125], s[2:3] op_sel_hi:[1,0]
	v_pk_mul_f32 v[118:119], v[118:119], s[2:3] op_sel_hi:[1,0]
	v_pk_mul_f32 v[120:121], v[120:121], s[2:3] op_sel_hi:[1,0]
	v_pk_mul_f32 v[114:115], v[114:115], s[2:3] op_sel_hi:[1,0]
	v_pk_mul_f32 v[116:117], v[116:117], s[2:3] op_sel_hi:[1,0]
	v_pk_mul_f32 v[110:111], v[110:111], s[2:3] op_sel_hi:[1,0]
	v_pk_mul_f32 v[112:113], v[112:113], s[2:3] op_sel_hi:[1,0]
	v_pk_mul_f32 v[106:107], v[106:107], s[2:3] op_sel_hi:[1,0]
	v_pk_mul_f32 v[108:109], v[108:109], s[2:3] op_sel_hi:[1,0]
	v_pk_mul_f32 v[102:103], v[102:103], s[2:3] op_sel_hi:[1,0]
	v_pk_mul_f32 v[104:105], v[104:105], s[2:3] op_sel_hi:[1,0]
	v_pk_mul_f32 v[98:99], v[98:99], s[2:3] op_sel_hi:[1,0]
	v_pk_mul_f32 v[100:101], v[100:101], s[2:3] op_sel_hi:[1,0]
	v_pk_mul_f32 v[94:95], v[94:95], s[2:3] op_sel_hi:[1,0]
	v_pk_mul_f32 v[96:97], v[96:97], s[2:3] op_sel_hi:[1,0]
	v_pk_mul_f32 v[90:91], v[90:91], s[2:3] op_sel_hi:[1,0]
	v_pk_mul_f32 v[92:93], v[92:93], s[2:3] op_sel_hi:[1,0]
	v_pk_mul_f32 v[86:87], v[86:87], s[2:3] op_sel_hi:[1,0]
	v_pk_mul_f32 v[88:89], v[88:89], s[2:3] op_sel_hi:[1,0]
	v_pk_mul_f32 v[82:83], v[82:83], s[2:3] op_sel_hi:[1,0]
	v_pk_mul_f32 v[84:85], v[84:85], s[2:3] op_sel_hi:[1,0]
	v_pk_mul_f32 v[78:79], v[78:79], s[2:3] op_sel_hi:[1,0]
	v_pk_mul_f32 v[80:81], v[80:81], s[2:3] op_sel_hi:[1,0]
	v_pk_mul_f32 v[74:75], v[74:75], s[2:3] op_sel_hi:[1,0]
	v_pk_mul_f32 v[76:77], v[76:77], s[2:3] op_sel_hi:[1,0]
	v_pk_mul_f32 v[70:71], v[70:71], s[2:3] op_sel_hi:[1,0]
	v_pk_mul_f32 v[72:73], v[72:73], s[2:3] op_sel_hi:[1,0]
	v_pk_mul_f32 v[66:67], v[66:67], s[2:3] op_sel_hi:[1,0]
	v_pk_mul_f32 v[68:69], v[68:69], s[2:3] op_sel_hi:[1,0]
	s_lshl_b64 s[0:1], s[4:5], 1
	s_add_u32 s0, s60, s0
	s_addc_u32 s1, s61, s1
	v_ashrrev_i32_e32 v131, 31, v130
	v_lshlrev_b64 v[130:131], 11, v[130:131]
	v_pk_mul_f32 v[62:63], v[62:63], s[2:3] op_sel_hi:[1,0]
	v_pk_mul_f32 v[64:65], v[64:65], s[2:3] op_sel_hi:[1,0]
	v_pk_mul_f32 v[58:59], v[58:59], s[2:3] op_sel_hi:[1,0]
	v_pk_mul_f32 v[60:61], v[60:61], s[2:3] op_sel_hi:[1,0]
	v_pk_mul_f32 v[54:55], v[54:55], s[2:3] op_sel_hi:[1,0]
	v_pk_mul_f32 v[56:57], v[56:57], s[2:3] op_sel_hi:[1,0]
	v_pk_mul_f32 v[50:51], v[50:51], s[2:3] op_sel_hi:[1,0]
	v_pk_mul_f32 v[52:53], v[52:53], s[2:3] op_sel_hi:[1,0]
	v_pk_mul_f32 v[46:47], v[46:47], s[2:3] op_sel_hi:[1,0]
	v_pk_mul_f32 v[48:49], v[48:49], s[2:3] op_sel_hi:[1,0]
	v_pk_mul_f32 v[42:43], v[42:43], s[2:3] op_sel_hi:[1,0]
	v_pk_mul_f32 v[44:45], v[44:45], s[2:3] op_sel_hi:[1,0]
	v_pk_mul_f32 v[38:39], v[38:39], s[2:3] op_sel_hi:[1,0]
	v_pk_mul_f32 v[40:41], v[40:41], s[2:3] op_sel_hi:[1,0]
	v_pk_mul_f32 v[34:35], v[34:35], s[2:3] op_sel_hi:[1,0]
	v_pk_mul_f32 v[36:37], v[36:37], s[2:3] op_sel_hi:[1,0]
	v_pk_mul_f32 v[30:31], v[30:31], s[2:3] op_sel_hi:[1,0]
	v_pk_mul_f32 v[32:33], v[32:33], s[2:3] op_sel_hi:[1,0]
	v_pk_mul_f32 v[26:27], v[26:27], s[2:3] op_sel_hi:[1,0]
	v_pk_mul_f32 v[28:29], v[28:29], s[2:3] op_sel_hi:[1,0]
	v_pk_mul_f32 v[22:23], v[22:23], s[2:3] op_sel_hi:[1,0]
	v_pk_mul_f32 v[24:25], v[24:25], s[2:3] op_sel_hi:[1,0]
	v_pk_mul_f32 v[18:19], v[18:19], s[2:3] op_sel_hi:[1,0]
	v_pk_mul_f32 v[20:21], v[20:21], s[2:3] op_sel_hi:[1,0]
	v_pk_mul_f32 v[14:15], v[14:15], s[2:3] op_sel_hi:[1,0]
	v_pk_mul_f32 v[16:17], v[16:17], s[2:3] op_sel_hi:[1,0]
	v_pk_mul_f32 v[10:11], v[10:11], s[2:3] op_sel_hi:[1,0]
	v_pk_mul_f32 v[12:13], v[12:13], s[2:3] op_sel_hi:[1,0]
	v_pk_mul_f32 v[6:7], v[6:7], s[2:3] op_sel_hi:[1,0]
	v_pk_mul_f32 v[8:9], v[8:9], s[2:3] op_sel_hi:[1,0]
	v_pk_mul_f32 v[2:3], v[2:3], s[2:3] op_sel_hi:[1,0]
	v_pk_mul_f32 v[4:5], v[4:5], s[2:3] op_sel_hi:[1,0]
	v_readlane_b32 s88, v254, 42
	v_readlane_b32 s89, v254, 43
	s_waitcnt vmcnt(7)
;     __device__ __forceinline__ bf16_t* G() const { return (bf16_t*)(ws + OFF_G); }
;     __device__ __forceinline__ bf16_t* Mb() const { return (bf16_t*)(ws + OFF_MB); }
; __device__ __forceinline__ unsigned pk2(float lo, float hi) { const f32x2_t f = {lo, hi}; const bf16x2_t b = __builtin_convertvector(f, bf16x2_t); return __builtin_bit_cast(unsigned, b); }
; #define LAS __attribute__((address_space(3)))
; __device__ __forceinline__ float ub(unsigned w, int j) { return (float)((w >> (8 * j)) & 0xffu); }
; template <bool PERMF = false, class F>
; __device__ __forceinline__ void epi_store_rows(LAS unsigned char* lds, int wid, int lane2, int fr, int fq, int wc, int mt, bf16_t* dbase, size_t dld, F getpk) {
;     LAS unsigned char* reg = lds + wid * 9216;
; #pragma unroll
;     for (int bj = 0; bj < 2; bj++)
; #pragma unroll
;         for (int n = 0; n < 2; n++)
; #pragma unroll
;             for (int m = 0; m < 4; m++) *(LAS u32x2*)(reg + ((bj * 2 + n) * 16 + fr) * LROW + (PERMF ? fq * 32 + m * 8 : fq * 8 + m * 32)) = getpk(bj, n, m);
; __device__ __forceinline__ void phase_gemm2(const Params& p, int layer, LAS unsigned char* lds) {
;     ...
;             epi_store_rows<true>(lds, wid, lane2, fr, fq, wc, mt, p.Mb() + f0, DM, [&](int bj, int n, int m) -> u32x2 {
;                 const int tk = mt * 256 + bj * 128 + wc * 32 + n * 16 + fr;
;                 const unsigned gw = *(const unsigned*)((const unsigned char*)p.G() + (size_t)tk * 3072 + 2048 + f0 + fq * 16 + m * 4);
;                 const f32x4 v = acc[ai][bj][m][n] * (1.f / 255.f);
;                 return (u32x2){pk2(v[0] * ub(gw, 0), v[1] * ub(gw, 1)), pk2(v[2] * ub(gw, 2), v[3] * ub(gw, 3))};
;             });
	v_cvt_f32_ubyte1_e32 v139, v192
	v_cvt_f32_ubyte0_e32 v138, v192
	v_pk_mul_f32 v[126:127], v[126:127], v[138:139]
	v_cvt_f32_ubyte3_e32 v139, v192
	v_cvt_f32_ubyte2_e32 v138, v192
	v_pk_mul_f32 v[128:129], v[128:129], v[138:139]
	v_cvt_pk_bf16_f32 v126, v126, v127
	v_cvt_pk_bf16_f32 v127, v128, v129
	v_cvt_f32_ubyte1_e32 v129, v193
	v_cvt_f32_ubyte0_e32 v128, v193
	v_pk_mul_f32 v[122:123], v[122:123], v[128:129]
	s_nop 0
	v_cvt_pk_bf16_f32 v128, v122, v123
	v_cvt_f32_ubyte3_e32 v123, v193
	v_cvt_f32_ubyte2_e32 v122, v193
	v_pk_mul_f32 v[122:123], v[124:125], v[122:123]
	s_nop 0
	v_cvt_pk_bf16_f32 v129, v122, v123
	v_cvt_f32_ubyte1_e32 v123, v194
	v_cvt_f32_ubyte0_e32 v122, v194
	v_pk_mul_f32 v[118:119], v[118:119], v[122:123]
	v_cvt_f32_ubyte3_e32 v123, v194
	v_cvt_f32_ubyte2_e32 v122, v194
	v_pk_mul_f32 v[120:121], v[120:121], v[122:123]
	v_cvt_pk_bf16_f32 v118, v118, v119
	v_cvt_pk_bf16_f32 v119, v120, v121
	v_cvt_f32_ubyte1_e32 v121, v195
	v_cvt_f32_ubyte0_e32 v120, v195
	v_pk_mul_f32 v[114:115], v[114:115], v[120:121]
	ds_write_b128 v155, v[126:129]
	v_cvt_pk_bf16_f32 v120, v114, v115
	v_cvt_f32_ubyte3_e32 v115, v195
	v_cvt_f32_ubyte2_e32 v114, v195
	v_pk_mul_f32 v[114:115], v[116:117], v[114:115]
	s_nop 0
	v_cvt_pk_bf16_f32 v121, v114, v115
	v_mad_i64_i32 v[114:115], s[6:7], v157, s90, v[152:153]
	v_lshl_add_u64 v[114:115], v[114:115], 0, s[4:5]
	v_lshl_add_u64 v[116:117], v[114:115], 0, v[0:1]
	v_lshl_add_u64 v[114:115], v[116:117], 0, s[8:9]
	v_add_co_u32_e32 v116, vcc, s81, v116
	ds_write_b128 v155, v[118:121] offset:16
	s_nop 0
	v_addc_co_u32_e32 v117, vcc, 0, v117, vcc
	s_waitcnt vmcnt(5)
	v_cvt_f32_ubyte1_e32 v121, v200
	v_cvt_f32_ubyte0_e32 v120, v200
	v_pk_mul_f32 v[110:111], v[110:111], v[120:121]
	v_cvt_f32_ubyte3_e32 v121, v200
	v_cvt_f32_ubyte2_e32 v120, v200
	v_pk_mul_f32 v[112:113], v[112:113], v[120:121]
	v_cvt_pk_bf16_f32 v110, v110, v111
	v_cvt_pk_bf16_f32 v111, v112, v113
	v_cvt_f32_ubyte1_e32 v113, v201
	v_cvt_f32_ubyte0_e32 v112, v201
	v_pk_mul_f32 v[106:107], v[106:107], v[112:113]
	s_nop 0
	v_cvt_pk_bf16_f32 v112, v106, v107
	v_cvt_f32_ubyte3_e32 v107, v201
	v_cvt_f32_ubyte2_e32 v106, v201
	v_pk_mul_f32 v[106:107], v[108:109], v[106:107]
	s_nop 0
	v_cvt_pk_bf16_f32 v113, v106, v107
	v_cvt_f32_ubyte1_e32 v107, v202
	v_cvt_f32_ubyte0_e32 v106, v202
	v_pk_mul_f32 v[102:103], v[102:103], v[106:107]
	v_cvt_f32_ubyte3_e32 v107, v202
	v_cvt_f32_ubyte2_e32 v106, v202
	v_pk_mul_f32 v[104:105], v[104:105], v[106:107]
	v_cvt_pk_bf16_f32 v102, v102, v103
	v_cvt_pk_bf16_f32 v103, v104, v105
	v_cvt_f32_ubyte1_e32 v105, v203
	v_cvt_f32_ubyte0_e32 v104, v203
	v_pk_mul_f32 v[98:99], v[98:99], v[104:105]
	ds_write_b128 v155, v[110:113] offset:2304
	v_cvt_pk_bf16_f32 v104, v98, v99
	v_cvt_f32_ubyte3_e32 v99, v203
	v_cvt_f32_ubyte2_e32 v98, v203
	v_pk_mul_f32 v[98:99], v[100:101], v[98:99]
	s_nop 0
	v_cvt_pk_bf16_f32 v105, v98, v99
	v_mad_i64_i32 v[98:99], s[6:7], v156, s90, v[152:153]
	v_lshl_add_u64 v[98:99], v[98:99], 0, s[4:5]
	v_lshl_add_u64 v[100:101], v[98:99], 0, v[0:1]
	v_lshl_add_u64 v[98:99], v[100:101], 0, s[8:9]
	v_add_co_u32_e32 v100, vcc, s81, v100
	ds_write_b128 v155, v[102:105] offset:2320
	s_nop 0
	v_addc_co_u32_e32 v101, vcc, 0, v101, vcc
	s_waitcnt vmcnt(3)
	v_cvt_f32_ubyte1_e32 v105, v208
	v_cvt_f32_ubyte0_e32 v104, v208
	v_pk_mul_f32 v[94:95], v[94:95], v[104:105]
	v_cvt_f32_ubyte3_e32 v105, v208
	v_cvt_f32_ubyte2_e32 v104, v208
	v_pk_mul_f32 v[96:97], v[96:97], v[104:105]
	v_cvt_pk_bf16_f32 v94, v94, v95
	v_cvt_pk_bf16_f32 v95, v96, v97
	v_cvt_f32_ubyte1_e32 v97, v209
	v_cvt_f32_ubyte0_e32 v96, v209
	v_pk_mul_f32 v[90:91], v[90:91], v[96:97]
	s_nop 0
	v_cvt_pk_bf16_f32 v96, v90, v91
	v_cvt_f32_ubyte3_e32 v91, v209
	v_cvt_f32_ubyte2_e32 v90, v209
	v_pk_mul_f32 v[90:91], v[92:93], v[90:91]
	s_nop 0
	v_cvt_pk_bf16_f32 v97, v90, v91
	v_cvt_f32_ubyte1_e32 v91, v210
	v_cvt_f32_ubyte0_e32 v90, v210
	v_pk_mul_f32 v[86:87], v[86:87], v[90:91]
	v_cvt_f32_ubyte3_e32 v91, v210
	v_cvt_f32_ubyte2_e32 v90, v210
	v_pk_mul_f32 v[88:89], v[88:89], v[90:91]
	v_cvt_pk_bf16_f32 v86, v86, v87
	v_cvt_pk_bf16_f32 v87, v88, v89
	v_cvt_f32_ubyte1_e32 v89, v211
	v_cvt_f32_ubyte0_e32 v88, v211
	v_pk_mul_f32 v[82:83], v[82:83], v[88:89]
	ds_write_b128 v155, v[94:97] offset:4608
	v_cvt_pk_bf16_f32 v88, v82, v83
	v_cvt_f32_ubyte3_e32 v83, v211
	v_cvt_f32_ubyte2_e32 v82, v211
	v_pk_mul_f32 v[82:83], v[84:85], v[82:83]
	s_nop 0
	v_cvt_pk_bf16_f32 v89, v82, v83
	v_mad_i64_i32 v[82:83], s[6:7], v149, s90, v[152:153]
	v_lshl_add_u64 v[82:83], v[82:83], 0, s[4:5]
	v_lshl_add_u64 v[82:83], v[82:83], 0, v[0:1]
	ds_write_b128 v155, v[86:89] offset:4624
	v_lshl_add_u64 v[86:87], v[82:83], 0, s[8:9]
	v_add_co_u32_e32 v82, vcc, s81, v82
	v_mov_b32_e32 v149, v1
	s_nop 0
	v_addc_co_u32_e32 v83, vcc, 0, v83, vcc
	s_waitcnt vmcnt(1)
; #define LAS __attribute__((address_space(3)))
; template <bool PERMF = false, class F>
; __device__ __forceinline__ void epi_store_rows(LAS unsigned char* lds, int wid, int lane2, int fr, int fq, int wc, int mt, bf16_t* dbase, size_t dld, F getpk) {
;     ...
;             for (int m = 0; m < 4; m++) *(LAS u32x2*)(reg + ((bj * 2 + n) * 16 + fr) * LROW + (PERMF ? fq * 32 + m * 8 : fq * 8 + m * 32)) = getpk(bj, n, m);
; #pragma unroll
;     for (int i = 0; i < 8; i++) {
;         const int c = lane2 + 64 * i, row = c >> 3, ch = c & 7;
;         const u32x4 w = *(const LAS u32x4*)(reg + row * LROW + ch * 16);
;         const int tk2 = mt * 256 + (row >> 5) * 128 + wc * 32 + (row & 31);
;         if (PERMF) *(u32x4*)(dbase + (size_t)tk2 * dld + ch * 8) = w;
;         else __builtin_nontemporal_store(w, (u32x4*)(dbase + (size_t)tk2 * dld + ch * 8));
;     }
	v_cvt_f32_ubyte1_e32 v89, v216
	v_cvt_f32_ubyte0_e32 v88, v216
	v_pk_mul_f32 v[78:79], v[78:79], v[88:89]
	v_cvt_f32_ubyte3_e32 v89, v216
	v_cvt_f32_ubyte2_e32 v88, v216
	v_pk_mul_f32 v[80:81], v[80:81], v[88:89]
	v_cvt_pk_bf16_f32 v78, v78, v79
	v_cvt_pk_bf16_f32 v79, v80, v81
	v_cvt_f32_ubyte1_e32 v81, v217
	v_cvt_f32_ubyte0_e32 v80, v217
	v_pk_mul_f32 v[74:75], v[74:75], v[80:81]
	v_lshl_add_u64 v[88:89], s[0:1], 0, v[148:149]
	v_cvt_pk_bf16_f32 v80, v74, v75
	v_cvt_f32_ubyte3_e32 v75, v217
	v_cvt_f32_ubyte2_e32 v74, v217
	v_pk_mul_f32 v[74:75], v[76:77], v[74:75]
	s_nop 0
	v_cvt_pk_bf16_f32 v81, v74, v75
	v_cvt_f32_ubyte1_e32 v75, v218
	v_cvt_f32_ubyte0_e32 v74, v218
	v_pk_mul_f32 v[70:71], v[70:71], v[74:75]
	v_cvt_f32_ubyte3_e32 v75, v218
	v_cvt_f32_ubyte2_e32 v74, v218
	v_pk_mul_f32 v[72:73], v[72:73], v[74:75]
	v_cvt_pk_bf16_f32 v70, v70, v71
	v_cvt_pk_bf16_f32 v71, v72, v73
	v_cvt_f32_ubyte1_e32 v73, v219
	v_cvt_f32_ubyte0_e32 v72, v219
	v_pk_mul_f32 v[66:67], v[66:67], v[72:73]
	ds_write_b128 v155, v[78:81] offset:6912
	v_cvt_pk_bf16_f32 v72, v66, v67
	v_cvt_f32_ubyte3_e32 v67, v219
	v_cvt_f32_ubyte2_e32 v66, v219
	v_pk_mul_f32 v[66:67], v[68:69], v[66:67]
	s_nop 0
	v_cvt_pk_bf16_f32 v73, v66, v67
	ds_write_b128 v155, v[70:73] offset:6928
	ds_read_b128 v[224:227], v154
	ds_read_b128 v[228:231], v154 offset:1152
	ds_read_b128 v[232:235], v154 offset:2304
	ds_read_b128 v[236:239], v154 offset:3456
	ds_read_b128 v[240:243], v154 offset:4608
	ds_read_b128 v[244:247], v154 offset:5760
	ds_read_b128 v[164:167], v154 offset:6912
	ds_read_b128 v[158:161], v154 offset:8064
	v_lshl_add_u64 v[66:67], v[88:89], 0, v[146:147]
	s_waitcnt lgkmcnt(7)
	s_waitcnt vmcnt(0)
	global_store_dwordx4 v[66:67], v[224:227], off
	s_nop 0
	v_lshl_add_u64 v[68:69], v[88:89], 0, v[144:145]
	s_waitcnt lgkmcnt(6)
	global_store_dwordx4 v[68:69], v[228:231], off
	s_nop 0
	v_lshl_add_u64 v[70:71], v[88:89], 0, v[142:143]
	s_waitcnt lgkmcnt(5)
	global_store_dwordx4 v[70:71], v[232:235], off
	s_nop 0
	v_lshl_add_u64 v[72:73], v[88:89], 0, v[140:141]
	s_waitcnt lgkmcnt(4)
	global_store_dwordx4 v[72:73], v[236:239], off
	s_nop 0
	v_lshl_add_u64 v[74:75], v[88:89], 0, v[136:137]
	s_waitcnt lgkmcnt(3)
	global_store_dwordx4 v[74:75], v[240:243], off
	s_nop 0
	v_lshl_add_u64 v[76:77], v[88:89], 0, v[134:135]
	s_waitcnt lgkmcnt(2)
	global_store_dwordx4 v[76:77], v[244:247], off
	s_nop 0
	v_lshl_add_u64 v[78:79], v[88:89], 0, v[132:133]
	s_waitcnt lgkmcnt(1)
	global_store_dwordx4 v[78:79], v[164:167], off
	s_nop 0
	v_lshl_add_u64 v[80:81], v[88:89], 0, v[130:131]
	s_waitcnt lgkmcnt(0)
;     __device__ __forceinline__ unsigned* BAR() const { return (unsigned*)(ws + OFF_BAR); }
; #define LAS __attribute__((address_space(3)))
; __device__ __forceinline__ unsigned xb_add(unsigned* p, unsigned v) { return __hip_atomic_fetch_add(p, v, __ATOMIC_RELAXED, __HIP_MEMORY_SCOPE_AGENT); }
; #define BAR __builtin_amdgcn_s_barrier()
; template <bool PERMF = false, class F>
; __device__ __forceinline__ void epi_store_rows(LAS unsigned char* lds, int wid, int lane2, int fr, int fq, int wc, int mt, bf16_t* dbase, size_t dld, F getpk) {
;     LAS unsigned char* reg = lds + wid * 9216;
; #pragma unroll
;     for (int bj = 0; bj < 2; bj++)
; #pragma unroll
;         for (int n = 0; n < 2; n++)
; #pragma unroll
;             for (int m = 0; m < 4; m++) *(LAS u32x2*)(reg + ((bj * 2 + n) * 16 + fr) * LROW + (PERMF ? fq * 32 + m * 8 : fq * 8 + m * 32)) = getpk(bj, n, m);
; #pragma unroll
;     for (int i = 0; i < 8; i++) {
;         const int c = lane2 + 64 * i, row = c >> 3, ch = c & 7;
;         const u32x4 w = *(const LAS u32x4*)(reg + row * LROW + ch * 16);
;         const int tk2 = mt * 256 + (row >> 5) * 128 + wc * 32 + (row & 31);
;         if (PERMF) *(u32x4*)(dbase + (size_t)tk2 * dld + ch * 8) = w;
;         else __builtin_nontemporal_store(w, (u32x4*)(dbase + (size_t)tk2 * dld + ch * 8));
;     }
; __device__ __forceinline__ void phase_gemm2(const Params& p, int layer, LAS unsigned char* lds) {
;     ...
;         asm volatile("s_waitcnt vmcnt(0)" ::: "memory");
;         __syncthreads();
;         if (threadIdx.x == 0) {
;             __builtin_amdgcn_fence(__ATOMIC_RELEASE, "agent");
;             asm volatile("s_waitcnt vmcnt(0)" ::: "memory");
;             xb_add(&p.BAR()[G23_PC(mt)], 1u);
;         }
	global_store_dwordx4 v[80:81], v[158:161], off
	v_cvt_f32_ubyte1_e32 v89, v196
	v_cvt_f32_ubyte0_e32 v88, v196
	v_pk_mul_f32 v[62:63], v[62:63], v[88:89]
	v_cvt_f32_ubyte3_e32 v89, v196
	v_cvt_f32_ubyte2_e32 v88, v196
	v_pk_mul_f32 v[64:65], v[64:65], v[88:89]
	v_cvt_pk_bf16_f32 v62, v62, v63
	v_cvt_pk_bf16_f32 v63, v64, v65
	v_cvt_f32_ubyte1_e32 v65, v197
	v_cvt_f32_ubyte0_e32 v64, v197
	v_pk_mul_f32 v[58:59], v[58:59], v[64:65]
	s_nop 0
	v_cvt_pk_bf16_f32 v64, v58, v59
	v_cvt_f32_ubyte3_e32 v59, v197
	v_cvt_f32_ubyte2_e32 v58, v197
	v_pk_mul_f32 v[58:59], v[60:61], v[58:59]
	s_nop 0
	v_cvt_pk_bf16_f32 v65, v58, v59
	v_cvt_f32_ubyte1_e32 v59, v198
	v_cvt_f32_ubyte0_e32 v58, v198
	v_pk_mul_f32 v[54:55], v[54:55], v[58:59]
	v_cvt_f32_ubyte3_e32 v59, v198
	v_cvt_f32_ubyte2_e32 v58, v198
	v_pk_mul_f32 v[56:57], v[56:57], v[58:59]
	v_cvt_pk_bf16_f32 v54, v54, v55
	v_cvt_pk_bf16_f32 v55, v56, v57
	v_cvt_f32_ubyte1_e32 v57, v199
	v_cvt_f32_ubyte0_e32 v56, v199
	v_pk_mul_f32 v[50:51], v[50:51], v[56:57]
	ds_write_b128 v155, v[62:65]
	v_cvt_pk_bf16_f32 v56, v50, v51
	v_cvt_f32_ubyte3_e32 v51, v199
	v_cvt_f32_ubyte2_e32 v50, v199
	v_pk_mul_f32 v[50:51], v[52:53], v[50:51]
	s_nop 0
	v_cvt_pk_bf16_f32 v57, v50, v51
	ds_write_b128 v155, v[54:57] offset:16
	v_cvt_f32_ubyte1_e32 v55, v204
	v_cvt_f32_ubyte0_e32 v54, v204
	v_pk_mul_f32 v[46:47], v[46:47], v[54:55]
	v_cvt_f32_ubyte3_e32 v55, v204
	v_cvt_f32_ubyte2_e32 v54, v204
	v_pk_mul_f32 v[48:49], v[48:49], v[54:55]
	v_cvt_pk_bf16_f32 v46, v46, v47
	v_cvt_pk_bf16_f32 v47, v48, v49
	v_cvt_f32_ubyte1_e32 v49, v205
	v_cvt_f32_ubyte0_e32 v48, v205
	v_pk_mul_f32 v[42:43], v[42:43], v[48:49]
	s_nop 0
	v_cvt_pk_bf16_f32 v48, v42, v43
	v_cvt_f32_ubyte3_e32 v43, v205
	v_cvt_f32_ubyte2_e32 v42, v205
	v_pk_mul_f32 v[42:43], v[44:45], v[42:43]
	s_nop 0
	v_cvt_pk_bf16_f32 v49, v42, v43
	v_cvt_f32_ubyte1_e32 v43, v206
	v_cvt_f32_ubyte0_e32 v42, v206
	v_pk_mul_f32 v[38:39], v[38:39], v[42:43]
	v_cvt_f32_ubyte3_e32 v43, v206
	v_cvt_f32_ubyte2_e32 v42, v206
	v_pk_mul_f32 v[40:41], v[40:41], v[42:43]
	v_cvt_pk_bf16_f32 v38, v38, v39
	v_cvt_pk_bf16_f32 v39, v40, v41
	v_cvt_f32_ubyte1_e32 v41, v207
	v_cvt_f32_ubyte0_e32 v40, v207
	v_pk_mul_f32 v[34:35], v[34:35], v[40:41]
	ds_write_b128 v155, v[46:49] offset:2304
	v_cvt_pk_bf16_f32 v40, v34, v35
	v_cvt_f32_ubyte3_e32 v35, v207
	v_cvt_f32_ubyte2_e32 v34, v207
	v_pk_mul_f32 v[34:35], v[36:37], v[34:35]
	s_nop 0
	v_cvt_pk_bf16_f32 v41, v34, v35
	ds_write_b128 v155, v[38:41] offset:2320
	v_cvt_f32_ubyte1_e32 v39, v212
	v_cvt_f32_ubyte0_e32 v38, v212
	v_pk_mul_f32 v[30:31], v[30:31], v[38:39]
	v_cvt_f32_ubyte3_e32 v39, v212
	v_cvt_f32_ubyte2_e32 v38, v212
	v_pk_mul_f32 v[32:33], v[32:33], v[38:39]
	v_cvt_pk_bf16_f32 v30, v30, v31
	v_cvt_pk_bf16_f32 v31, v32, v33
	v_cvt_f32_ubyte1_e32 v33, v213
	v_cvt_f32_ubyte0_e32 v32, v213
	v_pk_mul_f32 v[26:27], v[26:27], v[32:33]
	s_nop 0
	v_cvt_pk_bf16_f32 v32, v26, v27
	v_cvt_f32_ubyte3_e32 v27, v213
	v_cvt_f32_ubyte2_e32 v26, v213
	v_pk_mul_f32 v[26:27], v[28:29], v[26:27]
	s_nop 0
	v_cvt_pk_bf16_f32 v33, v26, v27
	v_cvt_f32_ubyte1_e32 v27, v214
	v_cvt_f32_ubyte0_e32 v26, v214
	v_pk_mul_f32 v[22:23], v[22:23], v[26:27]
	v_cvt_f32_ubyte3_e32 v27, v214
	v_cvt_f32_ubyte2_e32 v26, v214
	v_pk_mul_f32 v[24:25], v[24:25], v[26:27]
	v_cvt_pk_bf16_f32 v22, v22, v23
	v_cvt_pk_bf16_f32 v23, v24, v25
	v_cvt_f32_ubyte1_e32 v25, v215
	v_cvt_f32_ubyte0_e32 v24, v215
	v_pk_mul_f32 v[18:19], v[18:19], v[24:25]
	ds_write_b128 v155, v[30:33] offset:4608
	v_cvt_pk_bf16_f32 v24, v18, v19
	v_cvt_f32_ubyte3_e32 v19, v215
	v_cvt_f32_ubyte2_e32 v18, v215
	v_pk_mul_f32 v[18:19], v[20:21], v[18:19]
	s_nop 0
	v_cvt_pk_bf16_f32 v25, v18, v19
	ds_write_b128 v155, v[22:25] offset:4624
	v_cvt_f32_ubyte1_e32 v23, v220
	v_cvt_f32_ubyte0_e32 v22, v220
	v_pk_mul_f32 v[14:15], v[14:15], v[22:23]
	v_cvt_f32_ubyte3_e32 v23, v220
	v_cvt_f32_ubyte2_e32 v22, v220
	v_pk_mul_f32 v[16:17], v[16:17], v[22:23]
	v_cvt_pk_bf16_f32 v14, v14, v15
	v_cvt_pk_bf16_f32 v15, v16, v17
	v_cvt_f32_ubyte1_e32 v17, v221
	v_cvt_f32_ubyte0_e32 v16, v221
	v_pk_mul_f32 v[10:11], v[10:11], v[16:17]
	s_nop 0
	v_cvt_pk_bf16_f32 v16, v10, v11
	v_cvt_f32_ubyte3_e32 v11, v221
	v_cvt_f32_ubyte2_e32 v10, v221
	v_pk_mul_f32 v[10:11], v[12:13], v[10:11]
	s_nop 0
	v_cvt_pk_bf16_f32 v17, v10, v11
	v_cvt_f32_ubyte1_e32 v11, v222
	v_cvt_f32_ubyte0_e32 v10, v222
	v_pk_mul_f32 v[6:7], v[6:7], v[10:11]
	v_cvt_f32_ubyte3_e32 v11, v222
	v_cvt_f32_ubyte2_e32 v10, v222
	v_pk_mul_f32 v[8:9], v[8:9], v[10:11]
	v_cvt_pk_bf16_f32 v6, v6, v7
	v_cvt_pk_bf16_f32 v7, v8, v9
	v_cvt_f32_ubyte1_e32 v9, v223
	v_cvt_f32_ubyte0_e32 v8, v223
	v_pk_mul_f32 v[2:3], v[2:3], v[8:9]
	ds_write_b128 v155, v[14:17] offset:6912
	v_cvt_pk_bf16_f32 v8, v2, v3
	v_cvt_f32_ubyte3_e32 v3, v223
	v_cvt_f32_ubyte2_e32 v2, v223
	v_pk_mul_f32 v[2:3], v[4:5], v[2:3]
	s_nop 0
	v_cvt_pk_bf16_f32 v9, v2, v3
	ds_write_b128 v155, v[6:9] offset:6928
	ds_read_b128 v[224:227], v154
	ds_read_b128 v[228:231], v154 offset:1152
	ds_read_b128 v[232:235], v154 offset:2304
	ds_read_b128 v[236:239], v154 offset:3456
	ds_read_b128 v[240:243], v154 offset:4608
	ds_read_b128 v[244:247], v154 offset:5760
	ds_read_b128 v[164:167], v154 offset:6912
	ds_read_b128 v[158:161], v154 offset:8064
	s_waitcnt lgkmcnt(7)
	global_store_dwordx4 v[66:67], v[224:227], off offset:256
	s_waitcnt lgkmcnt(6)
	global_store_dwordx4 v[68:69], v[228:231], off offset:256
	s_waitcnt lgkmcnt(5)
	global_store_dwordx4 v[70:71], v[232:235], off offset:256
	s_waitcnt lgkmcnt(4)
	global_store_dwordx4 v[72:73], v[236:239], off offset:256
	s_waitcnt lgkmcnt(3)
	global_store_dwordx4 v[74:75], v[240:243], off offset:256
	s_waitcnt lgkmcnt(2)
	global_store_dwordx4 v[76:77], v[244:247], off offset:256
	s_waitcnt lgkmcnt(1)
	global_store_dwordx4 v[78:79], v[164:167], off offset:256
	s_waitcnt lgkmcnt(0)
	global_store_dwordx4 v[80:81], v[158:161], off offset:256
	s_waitcnt vmcnt(0)
	s_barrier
	s_and_saveexec_b64 s[0:1], s[88:89]
	s_cbranch_execz .LBB0_564
	s_mov_b64 s[4:5], exec
	v_mbcnt_lo_u32_b32 v0, s4, 0
	buffer_wbl2 sc1
	s_waitcnt vmcnt(0)
	s_waitcnt vmcnt(0)
	v_mbcnt_hi_u32_b32 v0, s5, v0
	v_cmp_eq_u32_e32 vcc, 0, v0
	s_and_b64 s[6:7], exec, vcc
	s_mov_b64 exec, s[6:7]
	s_cbranch_execz .LBB0_564
	s_lshl_b32 s6, s66, 6
	s_ashr_i32 s7, s6, 31
	s_lshl_b64 s[6:7], s[6:7], 2
	s_add_u32 s6, s20, s6
	s_addc_u32 s7, s21, s7
	s_bcnt1_i32_b64 s4, s[4:5]
	v_mov_b32_e32 v0, s4
	global_atomic_add v176, v0, s[6:7] offset:1792
	s_branch .LBB0_564
